# RWKV chunk loop VALU trim: folded tanh scale, copysign via v_bfi, dead rsqrt/log rescale code removed
# speedup vs baseline: 1.0211x; 1.0021x over previous
; #define LAS __attribute__((address_space(3)))
; __device__ __forceinline__ const float* INP(const Params& p, int i) { asm volatile("" : "+s"(i)); return p.in[i]; }
; __device__ __forceinline__ int BID() { int t = blockIdx.x; asm volatile("" : "+s"(t)); return t; }
; __device__ __forceinline__ int NBLK() { int t = gridDim.x; asm volatile("" : "+s"(t)); return t; }
; __device__ __forceinline__ unsigned char* WSP(const Params& p) { unsigned char* w = p.ws; asm volatile("" : "+s"(w)); return w; }
; __device__ __forceinline__ float* OUTP(const Params& p) { float* w = p.out; asm volatile("" : "+s"(w)); return w; }
; __global__ void __launch_bounds__(512, 2) fwd_kernel(Params p, int ph_lo, int ph_hi) {
;     extern __shared__ __attribute__((aligned(16))) unsigned char lds_raw[];
;     LAS unsigned char* lds = (LAS unsigned char*)lds_raw;
;     volatile LAS unsigned* bst = (volatile LAS unsigned*)(lds + 151552);
;     if (threadIdx.x < 4) bst[threadIdx.x] = 0u;
;     __syncthreads();
;     XcdBarrier xbar; xbar.bar = (unsigned*)p.ws; xbar.x = 0; xbar.st = bst;
;     if (ph_hi - ph_lo > 1) xbar = xcd_barrier_post((unsigned*)p.ws, bst);
;     for (int ph = ph_lo; ph < ph_hi; ++ph) {
;         const int G = NBLK(), c = BID();
;         unsigned char* ws = WSP(p); float* xo = OUTP(p);
;         bf16_t* W = (bf16_t*)(ws + WS_W); bf16_t* H = (bf16_t*)(ws + WS_H); bf16_t* ACT = (bf16_t*)(ws + WS_R);
;         if (ph == N_PHASES - 1) { rmsnorm_phase(xo, INP(p, 35), nullptr, xo); }
;         else {
;             const int l = ph / PH_PER_LAYER, k = ph % PH_PER_LAYER;
;             const float* xin = (l == 0) ? INP(p, 0) : xo;
;             switch (k) {
.LBB0_7:
	s_cmp_le_i32 s31, s30
	s_cbranch_scc1 .LBB0_944
	s_add_u32 s76, s0, 0x138
	s_addc_u32 s77, s1, 0
	s_add_u32 s82, s28, 0x200
	s_addc_u32 s83, s29, 0
	s_add_u32 s84, s28, 0x1000
	s_addc_u32 s85, s29, 0
	s_add_u32 s88, s28, 0x1100
	s_addc_u32 s89, s29, 0
	s_add_u32 s90, s28, 0x1200
	s_addc_u32 s91, s29, 0
	s_add_u32 s54, s28, 0x1300
	s_addc_u32 s55, s29, 0
	s_cmp_eq_u32 s6, 15
	s_cselect_b64 s[2:3], -1, 0
	s_cmp_eq_u32 s6, 14
	v_writelane_b32 v253, s2, 0
	v_lshrrev_b32_e32 v1, 20, v0
	v_lshrrev_b32_e32 v0, 10, v0
	v_writelane_b32 v253, s3, 1
	s_cselect_b64 s[2:3], -1, 0
	v_writelane_b32 v253, s2, 2
	s_cmp_eq_u32 s6, 13
	v_or_b32_e32 v0, v0, v1
	v_writelane_b32 v253, s3, 3
	s_cselect_b64 s[2:3], -1, 0
	v_writelane_b32 v253, s2, 4
	s_cmp_eq_u32 s6, 12
	s_load_dword s39, s[0:1], 0x138
	v_writelane_b32 v253, s3, 5
	s_cselect_b64 s[2:3], -1, 0
	v_writelane_b32 v253, s2, 6
	s_cmp_eq_u32 s6, 11
	v_mov_b32_e32 v1, 0
	v_writelane_b32 v253, s3, 7
	s_cselect_b64 s[2:3], -1, 0
	v_writelane_b32 v253, s2, 8
	s_cmp_eq_u32 s6, 10
	v_mbcnt_lo_u32_b32 v2, -1, 0
	v_writelane_b32 v253, s3, 9
	s_cselect_b64 s[2:3], -1, 0
	v_writelane_b32 v253, s2, 10
	s_cmp_eq_u32 s6, 9
	s_mov_b32 s58, 0x8000
	v_writelane_b32 v253, s3, 11
	s_cselect_b64 s[2:3], -1, 0
	v_writelane_b32 v253, s2, 12
	s_cmp_eq_u32 s6, 8
	v_mov_b64_e32 v[130:131], 0x200
	v_writelane_b32 v253, s3, 13
	s_cselect_b64 s[2:3], -1, 0
	v_writelane_b32 v253, s2, 14
	s_cmp_eq_u32 s6, 7
	v_mov_b64_e32 v[132:133], 0x1ff
	v_writelane_b32 v253, s3, 15
	s_cselect_b64 s[2:3], -1, 0
	v_writelane_b32 v253, s2, 16
	s_cmp_eq_u32 s6, 6
	s_mov_b32 s70, 0x80000
	v_writelane_b32 v253, s3, 17
	s_cselect_b64 s[2:3], -1, 0
	v_writelane_b32 v253, s2, 18
	s_cmp_eq_u32 s6, 5
	s_mov_b32 s71, 0x90000
	v_writelane_b32 v253, s3, 19
	s_cselect_b64 s[2:3], -1, 0
	v_writelane_b32 v253, s2, 20
	s_cmp_eq_u32 s6, 4
	s_mov_b32 s72, 0xa0000
	v_writelane_b32 v253, s3, 21
	s_cselect_b64 s[2:3], -1, 0
	v_writelane_b32 v253, s2, 22
	s_cmp_eq_u32 s6, 3
	s_movk_i32 s67, 0x1600
	v_writelane_b32 v253, s3, 23
	s_cselect_b64 s[2:3], -1, 0
	v_writelane_b32 v253, s2, 24
	s_cmp_eq_u32 s6, 2
	s_mov_b32 s97, 0xbfb8aa3b
	v_writelane_b32 v253, s3, 25
	s_cselect_b64 s[2:3], -1, 0
	v_writelane_b32 v253, s2, 26
	s_cmp_eq_u32 s6, 1
	v_mov_b32_e32 v169, 0x358637bd
	v_writelane_b32 v253, s3, 27
	s_cselect_b64 s[2:3], -1, 0
	v_writelane_b32 v253, s2, 28
	s_cmp_eq_u32 s6, 0
	s_mov_b32 s33, 0x800000
	v_writelane_b32 v253, s3, 29
	s_cselect_b64 s[2:3], -1, 0
	v_writelane_b32 v253, s2, 30
	s_movk_i32 s59, 0x7fff
	v_mov_b32_e32 v170, 0x3a27c5ac
	v_writelane_b32 v253, s3, 31
	s_lshl_b32 s2, s6, 8
	s_add_u32 s2, s28, s2
	s_addc_u32 s3, s29, 0
	s_add_u32 s4, s2, 0x1400
	s_addc_u32 s5, s3, 0
	s_add_u32 s56, s2, 0x2400
	s_addc_u32 s57, s3, 0
	v_writelane_b32 v253, s4, 32
	s_add_u32 s2, s28, 0x3400
	s_addc_u32 s3, s29, 0
	v_writelane_b32 v253, s5, 33
	v_writelane_b32 v253, s2, 34
	v_mov_b32_e32 v171, 0xbf1f24be
	v_mov_b32_e32 v172, 0x3e642e9d
	v_writelane_b32 v253, s3, 35
	s_add_u32 s2, s28, 0x3500
	s_addc_u32 s3, s29, 0
	v_writelane_b32 v253, s2, 36
	v_mov_b32_e32 v173, 1
	v_mov_b64_e32 v[134:135], 0xb00
	v_writelane_b32 v253, s3, 37
	s_movk_i32 s2, 0x3ff
	v_and_or_b32 v0, v0, s2, v168
	s_add_i32 s2, 0, 0x20800
	v_writelane_b32 v253, s2, 38
	s_add_i32 s2, 0, 0x11000
	v_writelane_b32 v253, s2, 39
	s_add_i32 s2, 0, 0x12200
	v_writelane_b32 v253, s2, 40
	s_add_i32 s2, 0, 0x13400
	v_writelane_b32 v253, s2, 41
	s_add_i32 s2, 0, 0x16c00
	v_writelane_b32 v253, s2, 42
	s_add_i32 s2, 0, 0x19400
	v_writelane_b32 v253, s2, 43
	s_add_i32 s2, 0, 0x1d000
	v_writelane_b32 v253, s2, 44
	s_add_i32 s2, 0, 0x1bc00
	v_writelane_b32 v253, s2, 45
	s_add_i32 s2, 0, 0x15800
	v_writelane_b32 v253, s2, 46
	s_add_i32 s2, 0, 0x14600
	v_writelane_b32 v253, s2, 47
	s_add_i32 s2, 0, 0x1da00
	v_writelane_b32 v253, s2, 48
	s_add_i32 s2, 0, 0x1f800
	v_writelane_b32 v253, s2, 49
	s_add_i32 s2, 0, 0x21600
	v_writelane_b32 v253, s2, 50
	s_add_i32 s2, 0, 0x1ee00
	v_writelane_b32 v253, s2, 51
	s_add_i32 s2, 0, 0x20200
	v_writelane_b32 v253, s2, 52
	s_add_i32 s2, 0, 0x20c00
	v_writelane_b32 v253, s2, 53
	s_add_i32 s2, 0, 0x1a800
	v_writelane_b32 v253, s2, 54
	s_add_i32 s2, 0, 0x22000
	v_writelane_b32 v253, s2, 55
	s_add_i32 s2, 0, 0x22a00
	v_writelane_b32 v253, s2, 56
	s_add_i32 s2, 0, 0xfe00
	v_writelane_b32 v253, s2, 57
	s_add_i32 s2, 0, 0x9200
	v_writelane_b32 v253, s2, 58
	s_add_i32 s2, 0, 0x15200
	v_writelane_b32 v253, s2, 59
	s_add_i32 s2, 0, 0x11800
	v_writelane_b32 v253, s2, 60
	s_add_i32 s2, 0, 0x18400
	v_writelane_b32 v253, s2, 61
	s_add_i32 s2, 0, 0x1cc00
	v_writelane_b32 v253, s2, 62
	s_add_i32 s2, 0, 0x18100
	v_writelane_b32 v253, s2, 63
	s_add_i32 s2, 0, 0x18200
	v_writelane_b32 v254, s2, 0
	s_add_i32 s2, 0, 0x1d800
	v_writelane_b32 v254, s2, 1
	s_add_i32 s2, 0, 0xf400
	v_writelane_b32 v254, s2, 2
	s_add_i32 s2, 0, 0x25000
	v_writelane_b32 v254, s2, 3
	s_add_i32 s2, 0, 0x25004
	v_writelane_b32 v254, s2, 4
	v_cmp_eq_u32_e64 s[2:3], 0, v168
	v_mov_b64_e32 v[136:137], 0xaff
	v_mbcnt_hi_u32_b32 v174, -1, v2
	v_writelane_b32 v254, s2, 5
	v_mov_b32_e32 v175, 0x3f80
	v_mov_b32_e32 v176, 0x41b17218
	v_writelane_b32 v254, s3, 6
	v_cmp_eq_u32_e64 s[2:3], 0, v0
	v_mov_b64_e32 v[140:141], 0x100
	v_mov_b64_e32 v[142:143], 0xff
	v_writelane_b32 v254, s2, 7
	v_mov_b32_e32 v177, 0xc40
	v_mov_b64_e32 v[144:145], 0x680
	v_writelane_b32 v254, s3, 8
	v_writelane_b32 v254, s54, 9
	v_mov_b64_e32 v[146:147], 0x67f
	v_mov_b32_e32 v252, 0x7fc00000
	v_writelane_b32 v254, s55, 10
	v_writelane_b32 v254, s56, 11
	s_movk_i32 s75, 0x7ff
	s_movk_i32 s46, 0xdc0
	v_writelane_b32 v254, s57, 12
	v_writelane_b32 v254, s73, 13
	v_writelane_b32 v254, s76, 14
	s_movk_i32 s47, 0xc40
	s_movk_i32 s43, 0x6ff
	v_writelane_b32 v254, s77, 15
	v_writelane_b32 v254, s82, 16
	s_mov_b32 s80, 0x66666667
	s_movk_i32 s81, 0xffd8
	v_writelane_b32 v254, s83, 17
	v_writelane_b32 v254, s84, 18
	s_mov_b32 s48, 0x3f317217
	s_mov_b32 s49, 0x7f800000
	v_writelane_b32 v254, s85, 19
	v_writelane_b32 v254, s88, 20
	s_mov_b32 s50, 0xb600
	s_mov_b32 s51, 0x38e38e39
	v_writelane_b32 v254, s89, 21
	v_writelane_b32 v254, s90, 22
	s_movk_i32 s52, 0xffb8
	s_movk_i32 s69, 0x6c00
	s_mov_b32 s68, s30
	s_mov_b32 s87, 0
	s_mov_b32 s98, 0xc038aa3b
	s_mov_b32 s99, 0x7fffffff
	s_mov_b64 s[26:27], 0x80
	s_mov_b64 s[36:37], 0x800
	s_mov_b32 s38, 0x3b000000
	s_mov_b32 s96, 0xbd800000
	s_mov_b32 s74, 0x3e000000
	v_writelane_b32 v254, s91, 23
	s_branch .LBB0_13

; #define LAS __attribute__((address_space(3)))
; __device__ __forceinline__ unsigned cvt_pk_bf16(float lo, float hi) { const f32x2_t v = {lo, hi}; const bf16x2_t b = __builtin_convertvector(v, bf16x2_t); return __builtin_bit_cast(unsigned, b); }
; __device__ __forceinline__ float tanh_(float x) { const float t = __expf(-2.0f * fabsf(x)); const float r = (1.0f - t) * __builtin_amdgcn_rcpf(1.0f + t); return x < 0.f ? -r : r; }
; #define LBAR() do { asm volatile("s_waitcnt lgkmcnt(0)" ::: "memory"); __builtin_amdgcn_s_barrier(); asm volatile("" ::: "memory"); } while (0)
; __device__ void rwkv_chunk_phase(const Params& p, int l, LAS unsigned char* lds) {
;     ...
;             for (int hf = 0; hf < 2; ++hf) { float fc[8], fp[8], fn[8]; unpack8(rc[hf], fc); unpack8(rp[hf], fp); unpack8(rn[hf], fn);
;                 const f32x4 m0 = *(const LAS f32x4*)(mu_s + cg * 16 + hf * 8), m1 = *(const LAS f32x4*)(mu_s + cg * 16 + hf * 8 + 4);
;                 f32x4 x0, x1;
; #pragma unroll
;                 for (int j = 0; j < 4; ++j) { x0[j] = fc[j] + m0[j] * (0.5f * (fp[j] + fn[j]) - fc[j]); x1[j] = fc[4 + j] + m1[j] * (0.5f * (fp[4 + j] + fn[4 + j]) - fc[4 + j]); }
;                 *(LAS f32x4*)(sh_s + tok * 256 + cg * 16 + hf * 8) = x0; *(LAS f32x4*)(sh_s + tok * 256 + cg * 16 + hf * 8 + 4) = x1; }
;             LBAR();
;             {   const int rt = wid >> 2, ct = wid & 3, row = rt * 16 + r16;
;                 const f32x4 d0 = *(const LAS f32x4*)(sh_s + row * 256 + 192 + quad * 8), d1 = *(const LAS f32x4*)(sh_s + row * 256 + 196 + quad * 8);
;                 const f32x4 e0 = *(const LAS f32x4*)(sh_s + row * 256 + 224 + quad * 8), e1 = *(const LAS f32x4*)(sh_s + row * 256 + 228 + quad * 8);
;                 u32x4 aw, aa;
;                 aw.x = cvt_pk_bf16(tanh_(d0[0]), tanh_(d0[1])); aw.y = cvt_pk_bf16(tanh_(d0[2]), tanh_(d0[3])); aw.z = cvt_pk_bf16(tanh_(d1[0]), tanh_(d1[1])); aw.w = cvt_pk_bf16(tanh_(d1[2]), tanh_(d1[3]));
;                 aa.x = cvt_pk_bf16(e0[0], e0[1]); aa.y = cvt_pk_bf16(e0[2], e0[3]); aa.z = cvt_pk_bf16(e1[0], e1[1]); aa.w = cvt_pk_bf16(e1[2], e1[3]);
;                 const bf16x8 bw = *(const LAS bf16x8*)(w2T + (ct * 16 + r16) * 40 + quad * 8), ba = *(const LAS bf16x8*)(a2T + (ct * 16 + r16) * 40 + quad * 8);
.Lrw_top:
	ds_read_b128 v[32:35], v206 offset:17664
	ds_read_b128 v[36:39], v206 offset:17680
	s_waitcnt vmcnt(1) lgkmcnt(0)
	v_lshlrev_b32_e32 v40, 16, v16
	v_and_b32_e32 v41, 0xffff0000, v16
	v_lshlrev_b32_e32 v42, 16, v24
	v_and_b32_e32 v43, 0xffff0000, v24
	v_lshlrev_b32_e32 v2, 16, v8
	v_and_b32_e32 v3, 0xffff0000, v8
	v_pk_add_f32 v[40:41], v[40:41], v[42:43]
	v_lshlrev_b32_e32 v42, 16, v26
	v_pk_fma_f32 v[40:41], v[40:41], 0.5, v[2:3] op_sel_hi:[1,0,1] neg_lo:[0,0,1] neg_hi:[0,0,1]
	v_and_b32_e32 v43, 0xffff0000, v26
	v_pk_fma_f32 v[32:33], v[40:41], v[32:33], v[2:3]
	v_lshlrev_b32_e32 v40, 16, v18
	v_and_b32_e32 v41, 0xffff0000, v18
	v_lshlrev_b32_e32 v2, 16, v10
	v_and_b32_e32 v3, 0xffff0000, v10
	v_pk_add_f32 v[40:41], v[40:41], v[42:43]
	v_lshlrev_b32_e32 v42, 16, v25
	v_pk_fma_f32 v[40:41], v[40:41], 0.5, v[2:3] op_sel_hi:[1,0,1] neg_lo:[0,0,1] neg_hi:[0,0,1]
	v_and_b32_e32 v43, 0xffff0000, v25
	v_pk_fma_f32 v[36:37], v[40:41], v[36:37], v[2:3]
	v_lshlrev_b32_e32 v40, 16, v17
	v_and_b32_e32 v41, 0xffff0000, v17
	v_lshlrev_b32_e32 v2, 16, v9
	v_and_b32_e32 v3, 0xffff0000, v9
	v_pk_add_f32 v[40:41], v[40:41], v[42:43]
	v_lshlrev_b32_e32 v42, 16, v27
	v_pk_fma_f32 v[40:41], v[40:41], 0.5, v[2:3] op_sel_hi:[1,0,1] neg_lo:[0,0,1] neg_hi:[0,0,1]
	v_and_b32_e32 v43, 0xffff0000, v27
	v_pk_fma_f32 v[34:35], v[40:41], v[34:35], v[2:3]
	v_lshlrev_b32_e32 v40, 16, v19
	v_and_b32_e32 v41, 0xffff0000, v19
	v_lshlrev_b32_e32 v2, 16, v11
	v_and_b32_e32 v3, 0xffff0000, v11
	v_pk_add_f32 v[40:41], v[40:41], v[42:43]
	v_lshlrev_b32_e32 v42, 16, v28
	v_pk_fma_f32 v[40:41], v[40:41], 0.5, v[2:3] op_sel_hi:[1,0,1] neg_lo:[0,0,1] neg_hi:[0,0,1]
	v_and_b32_e32 v43, 0xffff0000, v28
	v_pk_fma_f32 v[38:39], v[40:41], v[38:39], v[2:3]
	ds_write_b128 v87, v[32:35]
	ds_write_b128 v87, v[36:39] offset:16
	ds_read_b128 v[32:35], v206 offset:17696
	ds_read_b128 v[36:39], v206 offset:17712
	v_lshlrev_b32_e32 v40, 16, v20
	v_and_b32_e32 v41, 0xffff0000, v20
	v_lshlrev_b32_e32 v2, 16, v12
	v_and_b32_e32 v3, 0xffff0000, v12
	v_pk_add_f32 v[40:41], v[40:41], v[42:43]
	v_lshlrev_b32_e32 v42, 16, v30
	v_pk_fma_f32 v[40:41], v[40:41], 0.5, v[2:3] op_sel_hi:[1,0,1] neg_lo:[0,0,1] neg_hi:[0,0,1]
	v_and_b32_e32 v43, 0xffff0000, v30
	s_waitcnt lgkmcnt(1)
	v_pk_fma_f32 v[32:33], v[40:41], v[32:33], v[2:3]
	v_lshlrev_b32_e32 v40, 16, v22
	v_and_b32_e32 v41, 0xffff0000, v22
	v_lshlrev_b32_e32 v2, 16, v14
	v_and_b32_e32 v3, 0xffff0000, v14
	v_pk_add_f32 v[40:41], v[40:41], v[42:43]
	v_lshlrev_b32_e32 v42, 16, v29
	v_pk_fma_f32 v[40:41], v[40:41], 0.5, v[2:3] op_sel_hi:[1,0,1] neg_lo:[0,0,1] neg_hi:[0,0,1]
	v_and_b32_e32 v43, 0xffff0000, v29
	s_waitcnt lgkmcnt(0)
	v_pk_fma_f32 v[36:37], v[40:41], v[36:37], v[2:3]
	v_lshlrev_b32_e32 v40, 16, v21
	v_and_b32_e32 v41, 0xffff0000, v21
	v_lshlrev_b32_e32 v2, 16, v13
	v_and_b32_e32 v3, 0xffff0000, v13
	v_pk_add_f32 v[40:41], v[40:41], v[42:43]
	v_lshlrev_b32_e32 v42, 16, v31
	v_pk_fma_f32 v[40:41], v[40:41], 0.5, v[2:3] op_sel_hi:[1,0,1] neg_lo:[0,0,1] neg_hi:[0,0,1]
	v_and_b32_e32 v43, 0xffff0000, v31
	v_pk_fma_f32 v[34:35], v[40:41], v[34:35], v[2:3]
	v_lshlrev_b32_e32 v40, 16, v23
	v_and_b32_e32 v41, 0xffff0000, v23
	v_lshlrev_b32_e32 v2, 16, v15
	v_and_b32_e32 v3, 0xffff0000, v15
	v_pk_add_f32 v[40:41], v[40:41], v[42:43]
	s_add_i32 s62, s65, 1
	v_pk_fma_f32 v[40:41], v[40:41], 0.5, v[2:3] op_sel_hi:[1,0,1] neg_lo:[0,0,1] neg_hi:[0,0,1]
	s_nop 0
	v_pk_fma_f32 v[38:39], v[40:41], v[38:39], v[2:3]
	ds_write_b128 v87, v[32:35] offset:32
	ds_write_b128 v87, v[36:39] offset:48
	s_waitcnt lgkmcnt(0)
	s_barrier
	ds_read_b128 v[32:35], v89 offset:768
	ds_read_b128 v[36:39], v89 offset:784
	ds_read_b128 v[40:43], v89 offset:896
	s_waitcnt lgkmcnt(2)
	v_mul_f32_e64 v0, |v32|, s98
	v_exp_f32_e32 v2, v0
	v_mul_f32_e64 v0, |v33|, s98
	v_exp_f32_e32 v3, v0
	v_add_f32_e32 v0, 1.0, v2
	v_rcp_f32_e32 v44, v0
	v_add_f32_e32 v0, 1.0, v3
	v_rcp_f32_e32 v45, v0
	v_mul_f32_e64 v0, |v34|, s98
	v_pk_add_f32 v[2:3], v[2:3], 1.0 op_sel_hi:[1,0] neg_lo:[1,0] neg_hi:[1,0]
	v_pk_mul_f32 v[2:3], v[2:3], v[44:45]
	v_exp_f32_e32 v44, v0
	v_mul_f32_e64 v0, |v35|, s98
	v_exp_f32_e32 v45, v0
	v_bfi_b32 v0, s99, v3, v33
	v_add_f32_e32 v3, 1.0, v44
	v_rcp_f32_e32 v46, v3
	v_add_f32_e32 v3, 1.0, v45
	v_bfi_b32 v2, s99, v2, v32
	v_rcp_f32_e32 v47, v3
	v_cvt_pk_bf16_f32 v32, v2, v0
	s_waitcnt lgkmcnt(1)
	v_mul_f32_e64 v0, |v36|, s98
	v_pk_add_f32 v[2:3], v[44:45], 1.0 op_sel_hi:[1,0] neg_lo:[1,0] neg_hi:[1,0]
	v_exp_f32_e32 v44, v0
	v_mul_f32_e64 v0, |v37|, s98
	v_pk_mul_f32 v[2:3], v[2:3], v[46:47]
	v_exp_f32_e32 v45, v0
	s_waitcnt lgkmcnt(0)
	v_cvt_pk_bf16_f32 v40, v40, v41
	v_cvt_pk_bf16_f32 v41, v42, v43
	v_bfi_b32 v0, s99, v3, v35
	v_add_f32_e32 v3, 1.0, v44
	v_rcp_f32_e32 v46, v3
	v_bfi_b32 v2, s99, v2, v34
	v_cvt_pk_bf16_f32 v33, v2, v0
	v_mul_f32_e64 v0, |v38|, s98
	v_add_f32_e32 v3, 1.0, v45
	v_rcp_f32_e32 v47, v3
	v_pk_add_f32 v[2:3], v[44:45], 1.0 op_sel_hi:[1,0] neg_lo:[1,0] neg_hi:[1,0]
	v_exp_f32_e32 v44, v0
	v_mul_f32_e64 v0, |v39|, s98
	v_exp_f32_e32 v45, v0
	v_pk_mul_f32 v[2:3], v[2:3], v[46:47]
	v_bfi_b32 v0, s99, v3, v37
	v_add_f32_e32 v3, 1.0, v44
	v_rcp_f32_e32 v46, v3
	v_add_f32_e32 v3, 1.0, v45
	v_rcp_f32_e32 v47, v3
	v_bfi_b32 v2, s99, v2, v36
	v_cvt_pk_bf16_f32 v34, v2, v0
	v_pk_add_f32 v[2:3], v[44:45], 1.0 op_sel_hi:[1,0] neg_lo:[1,0] neg_hi:[1,0]
	v_pk_mul_f32 v[2:3], v[2:3], v[46:47]
	v_bfi_b32 v0, s99, v3, v39
	v_bfi_b32 v2, s99, v2, v38
	ds_read_b128 v[36:39], v91
	ds_read_b128 v[44:47], v89 offset:912
	v_cvt_pk_bf16_f32 v35, v2, v0
	ds_read_b128 v[58:61], v91 offset:5120
	ds_read2st64_b32 v[2:3], v207 offset0:64 offset1:65
	s_waitcnt lgkmcnt(3)
; #define LAS __attribute__((address_space(3)))
; __device__ __forceinline__ float bf_lo(unsigned w) { return __uint_as_float(w << 16); }
; __device__ void rwkv_chunk_phase(const Params& p, int l, LAS unsigned char* lds) {
;     ...
;                 const f32x4 cw = __builtin_amdgcn_mfma_f32_16x16x32_bf16(__builtin_bit_cast(bf16x8, aw), bw, z4, 0, 0, 0);
;                 const f32x4 ca = __builtin_amdgcn_mfma_f32_16x16x32_bf16(__builtin_bit_cast(bf16x8, aa), ba, z4, 0, 0, 0);
;                 const int col = ct * 16 + r16; const float w0c = c_s[col], a0c = c_s[64 + col];
;                 f32x4 lwv, lo;
; #pragma unroll
;                 for (int j = 0; j < 4; ++j) { const int tr_ = rt * 16 + quad * 4 + j; lwv[j] = -__expf(-softplus_(-(cw[j] + w0c)) - 0.5f); y_s[tr_ * 64 + col] = lwv[j]; lg_s[tr_ * 64 + col] = ca[j] + a0c; }
;                 const unsigned h01 = cvt_pk_bf16(lwv[0], lwv[1]), h23 = cvt_pk_bf16(lwv[2], lwv[3]);
;                 lo[0] = lwv[0] - bf_lo(h01); lo[1] = lwv[1] - bf_hi(h01); lo[2] = lwv[2] - bf_lo(h23); lo[3] = lwv[3] - bf_hi(h23);
;                 u32x2 hw; hw.x = h01; hw.y = h23; *(LAS u32x2*)(lwT_hi + col * 40 + rt * 16 + quad * 4) = hw; st_bf4(lwT_lo + col * 40 + rt * 16 + quad * 4, lo); }
;             LBAR();
;             {   const f32x4 wp = *(const LAS f32x4*)(y_s + tok * 64 + j0), ap = *(const LAS f32x4*)(lg_s + tok * 64 + j0);
;                 r4 = *(const LAS f32x4*)(sh_s + tok * 256 + j0); const f32x4 kv4 = *(const LAS f32x4*)(sh_s + tok * 256 + 64 + j0); v4 = *(const LAS f32x4*)(sh_s + tok * 256 + 128 + j0);
;                 float ss = 0.f, bs = 0.f;
; #pragma unroll
;                 for (int j = 0; j < 4; ++j) { kk4[j] = kv4[j] * c_s[128 + j0 + j]; ss += kk4[j] * kk4[j]; }
;                 ss = red16d(ss);
;                 const float rn_ = rsqrtf(ss + 1e-12f);
; #pragma unroll
;                 for (int j = 0; j < 4; ++j) {
;                     const float a = sigmoid_(ap[j]);
;                     lw4[j] = wp[j];
;                     kk4[j] *= rn_; b4[j] = kk4[j] * a;
;                     kd4[j] = kv4[j] * (1.0f + (a - 1.0f) * c_s[192 + j0 + j]);
;                     bs += r4[j] * kd4[j] * c_s[256 + j0 + j];
;                 }
;                 bs = red16d(bs);
;                 if (dir == 0 && cg == 0) BON[(t0 + tokm) * 8 + h] = bs;
	v_mfma_f32_16x16x32_bf16 v[32:35], v[32:35], v[36:39], 0
	s_waitcnt lgkmcnt(2)
	v_cvt_pk_bf16_f32 v42, v44, v45
	v_cvt_pk_bf16_f32 v43, v46, v47
	s_waitcnt lgkmcnt(0)
	s_nop 3
	v_add_f32_e32 v0, v32, v2
	v_mul_f32_e64 v32, |v0|, s97
	v_exp_f32_e32 v32, v32
	v_add_f32_e32 v33, v33, v2
	v_max_f32_e64 v0, -v0, 0
	v_add_f32_e32 v34, v34, v2
	v_add_f32_e32 v32, 1.0, v32
	v_add_f32_e32 v2, v35, v2
	v_mul_f32_e64 v35, |v2|, s97
	v_log_f32_e32 v32, v32
	v_mfma_f32_16x16x32_bf16 v[36:39], v[40:43], v[58:61], 0
	v_exp_f32_e32 v35, v35
	v_max_f32_e64 v2, -v2, 0
	v_mul_f32_e32 v40, 0x3f317217, v32
	v_fma_f32 v40, v32, s48, -v40
	v_fmac_f32_e32 v40, 0x3377d1cf, v32
	v_fmac_f32_e32 v40, 0x3f317217, v32
	v_add_f32_e32 v35, 1.0, v35
	v_add_f32_e32 v37, v37, v3
	v_mov_b32_e32 v32, v40
	v_mul_f32_e64 v40, |v33|, s97
	v_exp_f32_e32 v40, v40
	v_add_f32_e32 v0, v0, v32
	v_sub_f32_e32 v0, -0.5, v0
	v_mul_f32_e32 v0, 0x3fb8aa3b, v0
	v_add_f32_e32 v32, 1.0, v40
	v_max_f32_e64 v33, -v33, 0
	v_add_f32_e32 v38, v38, v3
	v_log_f32_e32 v40, v32
	v_exp_f32_e32 v32, v0
	v_add_f32_e32 v0, v36, v3
	v_add_f32_e32 v39, v39, v3
	v_mul_f32_e32 v36, 0x3f317217, v40
	v_fma_f32 v36, v40, s48, -v36
	v_fmac_f32_e32 v36, 0x3377d1cf, v40
	v_fmac_f32_e32 v36, 0x3f317217, v40
	v_mul_f32_e64 v40, |v34|, s97
	v_exp_f32_e32 v40, v40
	v_add_f32_e32 v33, v33, v36
	v_max_f32_e64 v34, -v34, 0
	v_sub_f32_e32 v33, -0.5, v33
	v_add_f32_e32 v36, 1.0, v40
	v_mul_f32_e32 v33, 0x3fb8aa3b, v33
	v_exp_f32_e32 v33, v33
	v_log_f32_e32 v36, v36
	s_nop 0
	v_mul_f32_e32 v40, 0x3f317217, v36
	v_fma_f32 v40, v36, s48, -v40
	v_fmac_f32_e32 v40, 0x3377d1cf, v36
	v_fmac_f32_e32 v40, 0x3f317217, v36
	v_mov_b32_e32 v36, v40
	v_add_f32_e32 v34, v34, v36
	v_sub_f32_e32 v34, -0.5, v34
	v_log_f32_e32 v35, v35
	v_mul_f32_e32 v34, 0x3fb8aa3b, v34
	v_exp_f32_e32 v34, v34
	v_xor_b32_e32 v40, 0x80000000, v32
	v_mul_f32_e32 v36, 0x3f317217, v35
	v_fma_f32 v36, v35, s48, -v36
	v_fmac_f32_e32 v36, 0x3377d1cf, v35
	v_fmac_f32_e32 v36, 0x3f317217, v35
	v_mov_b32_e32 v35, v36
	v_add_f32_e32 v2, v2, v35
	v_sub_f32_e32 v2, -0.5, v2
	v_mul_f32_e32 v2, 0x3fb8aa3b, v2
	v_exp_f32_e32 v35, v2
	v_pk_add_f32 v[2:3], v[32:33], 0 neg_lo:[1,1] neg_hi:[1,1]
	v_xor_b32_e32 v36, 0x80000000, v33
	v_cvt_pk_bf16_f32 v2, v2, v3
	ds_write2st64_b32 v148, v0, v40 offset0:82 offset1:114
	ds_write2st64_b32 v150, v37, v36 offset0:82 offset1:114
	v_lshlrev_b32_e32 v36, 16, v2
	v_and_b32_e32 v37, 0xffff0000, v2
	v_pk_add_f32 v[32:33], v[32:33], v[36:37] neg_lo:[1,1] neg_hi:[1,1]
	v_pk_add_f32 v[36:37], v[34:35], 0 neg_lo:[1,1] neg_hi:[1,1]
	v_xor_b32_e32 v3, 0x80000000, v34
	v_xor_b32_e32 v0, 0x80000000, v35
	ds_write2st64_b32 v152, v38, v3 offset0:82 offset1:114
	ds_write2st64_b32 v154, v39, v0 offset0:82 offset1:114
	v_cvt_pk_bf16_f32 v3, v36, v37
	v_lshlrev_b32_e32 v36, 16, v3
	v_and_b32_e32 v37, 0xffff0000, v3
	v_pk_add_f32 v[34:35], v[34:35], v[36:37] neg_lo:[1,1] neg_hi:[1,1]
	ds_write_b64 v92, v[2:3]
	v_cvt_pk_bf16_f32 v2, v32, v33
	v_cvt_pk_bf16_f32 v3, v34, v35
	ds_write_b64 v93, v[2:3]
	s_waitcnt lgkmcnt(0)
	s_barrier
	ds_read_b128 v[36:39], v94 offset:29184
	ds_read_b128 v[32:35], v94 offset:20992
	ds_read_b128 v[44:47], v96 offset:17408
	ds_read_b128 v[218:221], v96 offset:17152
	ds_read_b128 v[40:43], v95
	ds_read_b128 v[222:225], v95 offset:256
	s_and_b64 s[24:25], s[4:5], exec
	s_cselect_b32 s24, s62, s63
	s_lshl_b32 s24, s24, 5
	s_waitcnt lgkmcnt(4)
	v_mul_f32_e32 v0, 0xbfb8aa3b, v32
	v_exp_f32_e32 v0, v0
	v_mul_f32_e32 v2, 0xbfb8aa3b, v33
	v_exp_f32_e32 v2, v2
	s_or_b32 s24, s60, s24
	v_add_f32_e32 v0, 1.0, v0
	v_rcp_f32_e32 v64, v0
	v_add_f32_e32 v0, 1.0, v2
	v_rcp_f32_e32 v65, v0
	s_mov_b32 s25, s61
	v_lshl_add_u64 v[58:59], s[24:25], 0, v[52:53]
	v_pk_add_f32 v[2:3], v[64:65], -1.0 op_sel_hi:[1,0]
	s_waitcnt lgkmcnt(2)
	v_pk_fma_f32 v[2:3], v[2:3], v[218:219], 1.0 op_sel_hi:[1,1,0]
	s_waitcnt lgkmcnt(0)
	v_pk_mul_f32 v[62:63], v[222:223], v[2:3]
	v_mul_f32_e32 v3, 0xbfb8aa3b, v35
	v_mul_f32_e32 v0, v40, v62
	v_fma_f32 v0, v44, v0, 0
	v_mul_f32_e32 v2, v41, v63
	v_fmac_f32_e32 v0, v45, v2
	v_mul_f32_e32 v2, 0xbfb8aa3b, v34
	ds_read_b128 v[32:35], v95 offset:512
	ds_read_b128 v[226:229], v96 offset:16896
	v_exp_f32_e32 v2, v2
	v_exp_f32_e32 v3, v3
	v_add_f32_e32 v2, 1.0, v2
	s_waitcnt lgkmcnt(0)
	v_pk_mul_f32 v[70:71], v[222:223], v[226:227]
	v_rcp_f32_e32 v66, v2
	v_add_f32_e32 v2, 1.0, v3
	v_pk_mul_f32 v[68:69], v[224:225], v[228:229]
	v_pk_mul_f32 v[44:45], v[70:71], v[70:71]
	v_rcp_f32_e32 v67, v2
	v_pk_mul_f32 v[2:3], v[68:69], v[68:69]
	v_add_f32_e32 v44, v44, v45
	v_add_f32_e32 v2, v44, v2
	v_add_f32_e32 v2, v2, v3
	s_nop 1
	v_add_f32_dpp v2, v2, v2 quad_perm:[1,0,3,2] row_mask:0xf bank_mask:0xf bound_ctrl:1
	s_nop 1
	v_add_f32_dpp v2, v2, v2 quad_perm:[2,3,0,1] row_mask:0xf bank_mask:0xf bound_ctrl:1
	s_nop 1
	v_add_f32_dpp v51, v2, v2 row_half_mirror row_mask:0xf bank_mask:0xf bound_ctrl:1
	v_pk_add_f32 v[2:3], v[66:67], -1.0 op_sel_hi:[1,0]
	s_nop 0
	v_pk_fma_f32 v[2:3], v[2:3], v[220:221], 1.0 op_sel_hi:[1,1,0]
	v_mov_b32_dpp v218, v51 row_mirror row_mask:0xf bank_mask:0xf bound_ctrl:1
	v_pk_mul_f32 v[60:61], v[224:225], v[2:3]
	s_nop 0
	v_mul_f32_e32 v2, v42, v60
	v_fmac_f32_e32 v0, v46, v2
	v_mul_f32_e32 v2, v43, v61
	v_fmac_f32_e32 v0, v47, v2
	s_nop 1
	v_add_f32_dpp v0, v0, v0 quad_perm:[1,0,3,2] row_mask:0xf bank_mask:0xf bound_ctrl:1
	s_nop 1
	v_add_f32_dpp v0, v0, v0 quad_perm:[2,3,0,1] row_mask:0xf bank_mask:0xf bound_ctrl:1
	s_nop 1
	v_add_f32_dpp v0, v0, v0 row_half_mirror row_mask:0xf bank_mask:0xf bound_ctrl:1
	s_nop 1
	v_mov_b32_dpp v2, v0 row_mirror row_mask:0xf bank_mask:0xf bound_ctrl:1
	s_and_saveexec_b64 s[24:25], s[6:7]
	s_cbranch_execz .LBB0_323
	v_add_f32_e32 v0, v0, v2
	v_lshlrev_b64 v[2:3], 5, v[58:59]
	v_lshl_add_u64 v[2:3], s[40:41], 0, v[2:3]
	global_store_dword v[2:3], v0, off

; __device__ void rwkv_chunk_phase(const Params& p, int l, LAS unsigned char* lds) {
;     ...
;                 const float rn_ = rsqrtf(ss + 1e-12f);
; #pragma unroll
;                 for (int j = 0; j < 4; ++j) {
;                     const float a = sigmoid_(ap[j]);
;                     lw4[j] = wp[j];
;                     kk4[j] *= rn_; b4[j] = kk4[j] * a;
;                     kd4[j] = kv4[j] * (1.0f + (a - 1.0f) * c_s[192 + j0 + j]);
;                     bs += r4[j] * kd4[j] * c_s[256 + j0 + j];
;                 }
;                 bs = red16d(bs);
;                 if (dir == 0 && cg == 0) BON[(t0 + tokm) * 8 + h] = bs;
;             }
;             {
;                 const int rt = wid >> 2, ct = wid & 3; const f32x4 z4 = {0.f, 0.f, 0.f, 0.f};
;                 f32x4 acc = mm_nt<1>(L32, 40, rt * 16, lwT_hi, 40, ct * 16, r16, quad, z4);
;                 acc = mm_nt<1>(L32, 40, rt * 16, lwT_lo, 40, ct * 16, r16, quad, acc);
;                 const int col = ct * 16 + r16;
; #pragma unroll
;                 for (int j = 0; j < 4; ++j) lgp_s[(rt * 16 + quad * 4 + j) * 64 + col] = acc[j];
;                 if (rt == 1 && quad == 3) { tot_s[col] = acc[3]; gL_s[col] = __expf(acc[3]); } }
;             if (ci + 1 < 64 && rp_ == STG_REP - 1) { RW_LOAD(dir ? 62 - ci : ci + 1); }
;             LBAR();
;             {   const f32x4 lgl = *(const LAS f32x4*)(lgp_s + tok * 64 + j0), tot = *(const LAS f32x4*)(tot_s + j0);
;                 f32x4 ctv, btv, ktv, rtv, bgv, kgv;
; #pragma unroll
;                 for (int j = 0; j < 4; ++j) {
;                     const float lg = lgl[j], lgp = lg - lw4[j];
;                     const float einv = __expf(-lg), eL = __expf(tot[j] - lg);
;                     ctv[j] = kk4[j] * __expf(lgp); btv[j] = b4[j] * einv; ktv[j] = kd4[j] * einv; rtv[j] = r4[j] * __expf(dir ? lgp : lg);
;                     bgv[j] = b4[j] * eL; kgv[j] = kd4[j] * eL;
;                 }
;                 st_bf4(Ct + tok * 72 + j0, ctv); st_bf4(Bt + tok * 72 + j0, btv); st_bf4(Kt + tok * 72 + j0, ktv); st_bf4(Rt + tok * 72 + j0, rtv);
;                 st_bf4(BgT + tok * 72 + j0, bgv); st_bf4(KgT + tok * 72 + j0, kgv); st_bf4(VtT + tok * 72 + j0, v4);
;             }
;             }
;             LBAR();
; #pragma unroll
;             for (int i = 0; i < 2; ++i) { const int id = wid + 8 * i, pr = id >> 2, rt = (id >> 1) & 1, ct = id & 1;
.LBB0_331:
	v_add_f32_e32 v0, v51, v218
	v_add_f32_e32 v0, 0x2b8cbccc, v0
	s_waitcnt lgkmcnt(0)
	s_barrier
	ds_read_b128 v[44:47], v94 offset:55808
	v_rsq_f32_e32 v0, v0
	s_nop 0
	v_pk_mul_f32 v[2:3], v[70:71], v[0:1] op_sel_hi:[1,0]
	v_pk_mul_f32 v[138:139], v[68:69], v[0:1] op_sel_hi:[1,0]
	ds_read_b128 v[68:71], v96 offset:18944
	s_waitcnt lgkmcnt(0)
	v_sub_f32_e32 v0, v44, v36
	v_mul_f32_e32 v36, 0xbfb8aa3b, v44
	v_exp_f32_e32 v36, v36
	v_pk_mul_f32 v[64:65], v[64:65], v[2:3]
	v_sub_f32_e32 v51, v68, v44
	v_mul_f32_e32 v51, 0x3fb8aa3b, v51
	v_exp_f32_e32 v68, v51
	v_mul_f32_e32 v51, 0x3fb8aa3b, v0
	v_cndmask_b32_e64 v0, v44, v0, s[4:5]
	v_exp_f32_e32 v218, v51
	v_mul_f32_e32 v0, 0x3fb8aa3b, v0
	v_sub_f32_e32 v51, v69, v45
	v_exp_f32_e32 v44, v0
	v_sub_f32_e32 v0, v45, v37
	v_mul_f32_e32 v51, 0x3fb8aa3b, v51
	v_exp_f32_e32 v69, v51
	v_mul_f32_e32 v51, 0x3fb8aa3b, v0
	v_cndmask_b32_e64 v0, v45, v0, s[4:5]
	v_mul_f32_e32 v37, 0xbfb8aa3b, v45
	v_mul_f32_e32 v0, 0x3fb8aa3b, v0
	v_exp_f32_e32 v37, v37
	v_exp_f32_e32 v219, v51
	v_exp_f32_e32 v45, v0
	v_sub_f32_e32 v51, v70, v46
	v_sub_f32_e32 v0, v46, v38
	v_mul_f32_e32 v51, 0x3fb8aa3b, v51
	v_pk_mul_f32 v[2:3], v[2:3], v[218:219]
	v_pk_mul_f32 v[218:219], v[64:65], v[36:37]
	v_pk_mul_f32 v[40:41], v[40:41], v[44:45]
	v_pk_mul_f32 v[44:45], v[64:65], v[68:69]
	v_exp_f32_e32 v64, v51
	v_mul_f32_e32 v51, 0x3fb8aa3b, v0
	v_cndmask_b32_e64 v0, v46, v0, s[4:5]
	v_pk_mul_f32 v[36:37], v[62:63], v[36:37]
	v_pk_mul_f32 v[62:63], v[62:63], v[68:69]
	v_exp_f32_e32 v68, v51
	v_mul_f32_e32 v0, 0x3fb8aa3b, v0
	v_sub_f32_e32 v51, v71, v47
	v_mul_f32_e32 v38, 0xbfb8aa3b, v46
	v_exp_f32_e32 v46, v0
	v_sub_f32_e32 v0, v47, v39
	v_mul_f32_e32 v51, 0x3fb8aa3b, v51
	v_exp_f32_e32 v65, v51
	v_mul_f32_e32 v51, 0x3fb8aa3b, v0
	v_mul_f32_e32 v39, 0xbfb8aa3b, v47
	v_exp_f32_e32 v69, v51
	v_exp_f32_e32 v38, v38
	v_exp_f32_e32 v39, v39
	v_cndmask_b32_e64 v0, v47, v0, s[4:5]
	v_mul_f32_e32 v0, 0x3fb8aa3b, v0
	v_exp_f32_e32 v47, v0
	v_pk_mul_f32 v[66:67], v[66:67], v[138:139]
	v_pk_mul_f32 v[68:69], v[138:139], v[68:69]
	v_pk_mul_f32 v[70:71], v[66:67], v[38:39]
	v_cvt_pk_bf16_f32 v2, v2, v3
	v_cvt_pk_bf16_f32 v3, v68, v69
	v_pk_mul_f32 v[38:39], v[60:61], v[38:39]
	ds_write_b64 v101, v[2:3] offset:65024
	v_cvt_pk_bf16_f32 v2, v218, v219
	v_cvt_pk_bf16_f32 v3, v70, v71
	v_pk_mul_f32 v[42:43], v[42:43], v[46:47]
	ds_write_b64 v102, v[2:3]
	v_cvt_pk_bf16_f32 v2, v36, v37
	v_cvt_pk_bf16_f32 v3, v38, v39
	v_pk_mul_f32 v[46:47], v[66:67], v[64:65]
	ds_write_b64 v103, v[2:3]
	v_cvt_pk_bf16_f32 v2, v40, v41
	v_cvt_pk_bf16_f32 v3, v42, v43
	v_pk_mul_f32 v[60:61], v[60:61], v[64:65]
	ds_write_b64 v104, v[2:3]
	v_cvt_pk_bf16_f32 v2, v44, v45
	v_cvt_pk_bf16_f32 v3, v46, v47
	ds_write_b64 v105, v[2:3]
	v_cvt_pk_bf16_f32 v2, v62, v63
	v_cvt_pk_bf16_f32 v3, v60, v61
	ds_write_b64 v106, v[2:3]
	v_cvt_pk_bf16_f32 v2, v32, v33
	v_cvt_pk_bf16_f32 v3, v34, v35
	ds_write_b64 v107, v[2:3]
	s_waitcnt lgkmcnt(0)
	s_barrier
	ds_read_b128 v[32:35], v155
	ds_read_b128 v[36:39], v155 offset:64
	ds_read_b128 v[40:43], v156
	ds_read_b128 v[44:47], v156 offset:64
	s_waitcnt lgkmcnt(0)
	v_mfma_f32_16x16x32_bf16 v[32:35], v[32:35], v[40:43], 0
	v_mfma_f32_16x16x32_bf16 v[32:35], v[36:39], v[44:47], v[32:35]
	s_nop 7
	v_cndmask_b32_e64 v0, 0, v32, s[8:9]
	v_cndmask_b32_e64 v3, v33, 0, s[10:11]
	v_cndmask_b32_e64 v2, 0, v34, s[12:13]
	v_cndmask_b32_e64 v32, 0, v35, s[14:15]
	s_and_saveexec_b64 s[24:25], s[72:73]
	s_xor_b64 s[24:25], exec, s[24:25]
	v_cvt_pk_bf16_f32 v34, v0, v3
	v_cvt_pk_bf16_f32 v35, v2, v32
	ds_write_b64 v158, v[34:35]
	s_andn2_saveexec_b64 s[24:25], s[24:25]
	s_cbranch_execz .LBB0_335
	v_sub_f32_e32 v33, v159, v0
	v_sub_f32_e32 v35, v161, v2
	v_sub_f32_e32 v36, v162, v32
	v_xor_b32_e32 v32, 0x80000000, v32
	v_xor_b32_e32 v37, 0x80000000, v2
	v_xor_b32_e32 v2, 0x80000000, v3
	v_xor_b32_e32 v0, 0x80000000, v0
	v_sub_f32_e32 v34, v160, v3
	v_cvt_pk_bf16_f32 v2, v0, v2
	v_cvt_pk_bf16_f32 v3, v37, v32
	ds_write_b64 v111, v[2:3]
	v_cvt_pk_bf16_f32 v2, v33, v34
	v_cvt_pk_bf16_f32 v3, v35, v36
	ds_write_b64 v112, v[2:3]

; __global__ void __launch_bounds__(512, 2) fwd_kernel(Params p, int ph_lo, int ph_hi) {
;     extern __shared__ __attribute__((aligned(16))) unsigned char lds_raw[];
	.amdhsa_kernel _Z10fwd_kernel6Paramsii
		.amdhsa_group_segment_fixed_size 0
		.amdhsa_private_segment_fixed_size 0
		.amdhsa_kernarg_size 568
		.amdhsa_user_sgpr_count 2
		.amdhsa_user_sgpr_dispatch_ptr 0
		.amdhsa_user_sgpr_queue_ptr 0
		.amdhsa_user_sgpr_kernarg_segment_ptr 1
		.amdhsa_user_sgpr_dispatch_id 0
		.amdhsa_user_sgpr_kernarg_preload_length 0
		.amdhsa_user_sgpr_kernarg_preload_offset 0
		.amdhsa_user_sgpr_private_segment_size 0
		.amdhsa_uses_dynamic_stack 0
		.amdhsa_enable_private_segment 0
		.amdhsa_system_sgpr_workgroup_id_x 1
		.amdhsa_system_sgpr_workgroup_id_y 0
		.amdhsa_system_sgpr_workgroup_id_z 0
		.amdhsa_system_sgpr_workgroup_info 0
		.amdhsa_system_vgpr_workitem_id 2
		.amdhsa_next_free_vgpr 256
		.amdhsa_next_free_sgpr 100
		.amdhsa_accum_offset 256
		.amdhsa_reserve_vcc 1
		.amdhsa_float_round_mode_32 0
		.amdhsa_float_round_mode_16_64 0
		.amdhsa_float_denorm_mode_32 3
		.amdhsa_float_denorm_mode_16_64 3
		.amdhsa_dx10_clamp 1
		.amdhsa_ieee_mode 1
		.amdhsa_fp16_overflow 0
		.amdhsa_tg_split 0
		.amdhsa_exception_fp_ieee_invalid_op 0
		.amdhsa_exception_fp_denorm_src 0
		.amdhsa_exception_fp_ieee_div_zero 0
		.amdhsa_exception_fp_ieee_overflow 0
		.amdhsa_exception_fp_ieee_underflow 0
		.amdhsa_exception_fp_ieee_inexact 0
		.amdhsa_exception_int_div_zero 0
	.end_amdhsa_kernel

; __global__ void __launch_bounds__(512, 2) fwd_kernel(Params p, int ph_lo, int ph_hi) {
;     extern __shared__ __attribute__((aligned(16))) unsigned char lds_raw[];
amdhsa.kernels:
  - .agpr_count:     0
    .args:
      - .offset:         0
        .size:           304
        .value_kind:     by_value
      - .offset:         304
        .size:           4
        .value_kind:     by_value
      - .offset:         308
        .size:           4
        .value_kind:     by_value
      - .offset:         312
        .size:           4
        .value_kind:     hidden_block_count_x
      - .offset:         316
        .size:           4
        .value_kind:     hidden_block_count_y
      - .offset:         320
        .size:           4
        .value_kind:     hidden_block_count_z
      - .offset:         324
        .size:           2
        .value_kind:     hidden_group_size_x
      - .offset:         326
        .size:           2
        .value_kind:     hidden_group_size_y
      - .offset:         328
        .size:           2
        .value_kind:     hidden_group_size_z
      - .offset:         330
        .size:           2
        .value_kind:     hidden_remainder_x
      - .offset:         332
        .size:           2
        .value_kind:     hidden_remainder_y
      - .offset:         334
        .size:           2
        .value_kind:     hidden_remainder_z
      - .offset:         352
        .size:           8
        .value_kind:     hidden_global_offset_x
      - .offset:         360
        .size:           8
        .value_kind:     hidden_global_offset_y
      - .offset:         368
        .size:           8
        .value_kind:     hidden_global_offset_z
      - .offset:         376
        .size:           2
        .value_kind:     hidden_grid_dims
      - .offset:         400
        .size:           8
        .value_kind:     hidden_multigrid_sync_arg
      - .offset:         432
        .size:           4
        .value_kind:     hidden_dynamic_lds_size
    .group_segment_fixed_size: 0
    .kernarg_segment_align: 8
    .kernarg_segment_size: 568
    .language:       OpenCL C
    .language_version:
      - 2
      - 0
    .max_flat_workgroup_size: 512
    .name:           _Z10fwd_kernel6Paramsii
    .private_segment_fixed_size: 0
    .sgpr_count:     106
    .sgpr_spill_count: 169
    .symbol:         _Z10fwd_kernel6Paramsii.kd
    .uniform_work_group_size: 1
    .uses_dynamic_stack: false
    .vgpr_count:     256
    .vgpr_spill_count: 0
    .wavefront_size: 64
